# attention-tail weight conversion: two items per trip, second item's loads in flight while the first is transposed
# speedup vs baseline: 1.0019x; 1.0019x over previous
.Lcva_loop:
	s_lshr_b32 s12, s35, s22
	s_lshl_b32 s13, 1, s22
	s_add_i32 s13, s13, -1
	s_and_b32 s13, s35, s13
	s_add_i32 s14, s22, -4
	s_lshr_b32 s15, s13, s14
	s_add_i32 s18, s25, -1
	s_and_b32 s18, s13, s18
	s_mov_b64 s[20:21], s[6:7]
	s_mov_b32 s19, 0x8000
	s_mov_b64 s[36:37], s[48:49]
	s_mov_b32 s98, 0x3e0293ee
	s_mov_b32 s14, 0
	s_cmp_eq_u32 s12, 0
	s_cbranch_scc1 .LcvaA_sel
	s_mov_b32 s98, 1.0
	s_cmp_eq_u32 s12, 1
	s_cbranch_scc0 .LcvaA_s2
	s_mov_b64 s[20:21], s[0:1]
	s_mov_b32 s19, 0xc000
	s_mov_b64 s[36:37], s[44:45]
	s_mov_b32 s14, s24
	s_branch .LcvaA_sel

.LcvaA_sel:
	v_mov_b32_e32 v56, s98
	s_lshl_b32 s12, s15, 6
	s_mul_i32 s12, s12, s19
	s_lshl_b32 s13, s18, 7
	s_add_u32 s12, s12, s13
	s_add_u32 s98, s20, s12
	s_addc_u32 s99, s21, 0
	s_lshl_b32 s100, s19, 3
	s_mov_b32 s101, 0
	v_mul_u32_u24_e32 v3, s19, v1
	v_lshl_add_u32 v12, v2, 4, v3
	v_lshl_add_u64 v[4:5], s[98:99], 0, v[12:13]
	global_load_dwordx4 v[16:19], v[4:5], off
	v_lshl_add_u64 v[4:5], s[100:101], 0, v[4:5]
	global_load_dwordx4 v[20:23], v[4:5], off
	v_lshl_add_u64 v[4:5], s[100:101], 0, v[4:5]
	global_load_dwordx4 v[24:27], v[4:5], off
	v_lshl_add_u64 v[4:5], s[100:101], 0, v[4:5]
	global_load_dwordx4 v[28:31], v[4:5], off
	v_lshl_add_u64 v[4:5], s[100:101], 0, v[4:5]
	global_load_dwordx4 v[32:35], v[4:5], off
	v_lshl_add_u64 v[4:5], s[100:101], 0, v[4:5]
	global_load_dwordx4 v[36:39], v[4:5], off
	v_lshl_add_u64 v[4:5], s[100:101], 0, v[4:5]
	global_load_dwordx4 v[40:43], v[4:5], off
	v_lshl_add_u64 v[4:5], s[100:101], 0, v[4:5]
	global_load_dwordx4 v[44:47], v[4:5], off
	s_lshl_b32 s12, s15, 8
	v_lshl_add_u32 v12, v1, 2, s12
	v_lshl_add_u64 v[6:7], s[36:37], 0, v[12:13]
	global_load_dword v48, v[6:7], off
	global_load_dword v49, v[6:7], off offset:32
	global_load_dword v50, v[6:7], off offset:64
	global_load_dword v51, v[6:7], off offset:96
	global_load_dword v52, v[6:7], off offset:128
	global_load_dword v53, v[6:7], off offset:160
	global_load_dword v54, v[6:7], off offset:192
	global_load_dword v55, v[6:7], off offset:224
	s_lshl_b32 s13, s18, 5
	s_add_i32 s13, s13, s14
	s_lshl_b32 s13, s13, 11
	s_lshl_b32 s12, s15, 7
	s_add_u32 s13, s13, s12
	s_add_u32 s98, s42, s13
	s_addc_u32 s99, s43, 0
	v_lshl_add_u64 v[14:15], s[98:99], 0, v[10:11]
	s_add_i32 s38, s35, s39
	s_cmp_lt_i32 s38, s23
	s_cbranch_scc0 .Lcva_single
	s_lshr_b32 s12, s38, s22
	s_lshl_b32 s13, 1, s22
	s_add_i32 s13, s13, -1
	s_and_b32 s13, s38, s13
	s_add_i32 s14, s22, -4
	s_lshr_b32 s15, s13, s14
	s_add_i32 s18, s25, -1
	s_and_b32 s18, s13, s18
	s_mov_b64 s[20:21], s[6:7]
	s_mov_b32 s19, 0x8000
	s_mov_b64 s[36:37], s[48:49]
	s_mov_b32 s98, 0x3e0293ee
	s_mov_b32 s14, 0
	s_cmp_eq_u32 s12, 0
	s_cbranch_scc1 .LcvaB_sel
	s_mov_b32 s98, 1.0
	s_cmp_eq_u32 s12, 1
	s_cbranch_scc0 .LcvaB_s2
	s_mov_b64 s[20:21], s[0:1]
	s_mov_b32 s19, 0xc000
	s_mov_b64 s[36:37], s[44:45]
	s_mov_b32 s14, s24
	s_branch .LcvaB_sel

.LcvaB_sel:
	v_mov_b32_e32 v104, s98
	s_lshl_b32 s12, s15, 6
	s_mul_i32 s12, s12, s19
	s_lshl_b32 s13, s18, 7
	s_add_u32 s12, s12, s13
	s_add_u32 s98, s20, s12
	s_addc_u32 s99, s21, 0
	s_lshl_b32 s100, s19, 3
	s_mov_b32 s101, 0
	v_mul_u32_u24_e32 v3, s19, v1
	v_lshl_add_u32 v12, v2, 4, v3
	v_lshl_add_u64 v[4:5], s[98:99], 0, v[12:13]
	global_load_dwordx4 v[64:67], v[4:5], off
	v_lshl_add_u64 v[4:5], s[100:101], 0, v[4:5]
	global_load_dwordx4 v[68:71], v[4:5], off
	v_lshl_add_u64 v[4:5], s[100:101], 0, v[4:5]
	global_load_dwordx4 v[72:75], v[4:5], off
	v_lshl_add_u64 v[4:5], s[100:101], 0, v[4:5]
	global_load_dwordx4 v[76:79], v[4:5], off
	v_lshl_add_u64 v[4:5], s[100:101], 0, v[4:5]
	global_load_dwordx4 v[80:83], v[4:5], off
	v_lshl_add_u64 v[4:5], s[100:101], 0, v[4:5]
	global_load_dwordx4 v[84:87], v[4:5], off
	v_lshl_add_u64 v[4:5], s[100:101], 0, v[4:5]
	global_load_dwordx4 v[88:91], v[4:5], off
	v_lshl_add_u64 v[4:5], s[100:101], 0, v[4:5]
	global_load_dwordx4 v[92:95], v[4:5], off
	s_lshl_b32 s12, s15, 8
	v_lshl_add_u32 v12, v1, 2, s12
	v_lshl_add_u64 v[6:7], s[36:37], 0, v[12:13]
	global_load_dword v96, v[6:7], off
	global_load_dword v97, v[6:7], off offset:32
	global_load_dword v98, v[6:7], off offset:64
	global_load_dword v99, v[6:7], off offset:96
	global_load_dword v100, v[6:7], off offset:128
	global_load_dword v101, v[6:7], off offset:160
	global_load_dword v102, v[6:7], off offset:192
	global_load_dword v103, v[6:7], off offset:224
	s_lshl_b32 s13, s18, 5
	s_add_i32 s13, s13, s14
	s_lshl_b32 s13, s13, 11
	s_lshl_b32 s12, s15, 7
	s_add_u32 s13, s13, s12
	s_add_u32 s98, s42, s13
	s_addc_u32 s99, s43, 0
	v_lshl_add_u64 v[60:61], s[98:99], 0, v[10:11]
	s_movk_i32 s100, 0x4000
	s_waitcnt vmcnt(16)
	v_mul_f32_e32 v48, v56, v48
	v_mul_f32_e32 v49, v56, v49
	v_mul_f32_e32 v50, v56, v50
	v_mul_f32_e32 v51, v56, v51
	v_mul_f32_e32 v52, v56, v52
	v_mul_f32_e32 v53, v56, v53
	v_mul_f32_e32 v54, v56, v54
	v_mul_f32_e32 v55, v56, v55
	v_mul_f32_e32 v16, v16, v48
	v_mul_f32_e32 v17, v17, v48
	v_mul_f32_e32 v18, v18, v48
	v_mul_f32_e32 v19, v19, v48
	v_mul_f32_e32 v20, v20, v49
	v_mul_f32_e32 v21, v21, v49
	v_mul_f32_e32 v22, v22, v49
	v_mul_f32_e32 v23, v23, v49
	v_mul_f32_e32 v24, v24, v50
	v_mul_f32_e32 v25, v25, v50
	v_mul_f32_e32 v26, v26, v50
	v_mul_f32_e32 v27, v27, v50
	v_mul_f32_e32 v28, v28, v51
	v_mul_f32_e32 v29, v29, v51
	v_mul_f32_e32 v30, v30, v51
	v_mul_f32_e32 v31, v31, v51
	v_mul_f32_e32 v32, v32, v52
	v_mul_f32_e32 v33, v33, v52
	v_mul_f32_e32 v34, v34, v52
	v_mul_f32_e32 v35, v35, v52
	v_mul_f32_e32 v36, v36, v53
	v_mul_f32_e32 v37, v37, v53
	v_mul_f32_e32 v38, v38, v53
	v_mul_f32_e32 v39, v39, v53
	v_mul_f32_e32 v40, v40, v54
	v_mul_f32_e32 v41, v41, v54
	v_mul_f32_e32 v42, v42, v54
	v_mul_f32_e32 v43, v43, v54
	v_mul_f32_e32 v44, v44, v55
	v_mul_f32_e32 v45, v45, v55
	v_mul_f32_e32 v46, v46, v55
	v_mul_f32_e32 v47, v47, v55
	ds_write_b32 v8, v16 offset:0
	ds_write_b32 v8, v17 offset:4
	ds_write_b32 v8, v18 offset:8
	ds_write_b32 v8, v19 offset:12
	ds_write_b32 v8, v20 offset:1056
	ds_write_b32 v8, v21 offset:1060
	ds_write_b32 v8, v22 offset:1064
	ds_write_b32 v8, v23 offset:1068
	ds_write_b32 v8, v24 offset:2112
	ds_write_b32 v8, v25 offset:2116
	ds_write_b32 v8, v26 offset:2120
	ds_write_b32 v8, v27 offset:2124
	ds_write_b32 v8, v28 offset:3168
	ds_write_b32 v8, v29 offset:3172
	ds_write_b32 v8, v30 offset:3176
	ds_write_b32 v8, v31 offset:3180
	ds_write_b32 v8, v32 offset:4224
	ds_write_b32 v8, v33 offset:4228
	ds_write_b32 v8, v34 offset:4232
	ds_write_b32 v8, v35 offset:4236
	ds_write_b32 v8, v36 offset:5280
	ds_write_b32 v8, v37 offset:5284
	ds_write_b32 v8, v38 offset:5288
	ds_write_b32 v8, v39 offset:5292
	ds_write_b32 v8, v40 offset:6336
	ds_write_b32 v8, v41 offset:6340
	ds_write_b32 v8, v42 offset:6344
	ds_write_b32 v8, v43 offset:6348
	ds_write_b32 v8, v44 offset:7392
	ds_write_b32 v8, v45 offset:7396
	ds_write_b32 v8, v46 offset:7400
	ds_write_b32 v8, v47 offset:7404
	s_waitcnt lgkmcnt(0)
	ds_read_b32 v16, v9 offset:0
	ds_read_b32 v17, v9 offset:132
	ds_read_b32 v18, v9 offset:264
	ds_read_b32 v19, v9 offset:396
	ds_read_b32 v20, v9 offset:528
	ds_read_b32 v21, v9 offset:660
	ds_read_b32 v22, v9 offset:792
	ds_read_b32 v23, v9 offset:924
	s_waitcnt lgkmcnt(0)
	v_cvt_pk_bf16_f32 v108, v16, v17
	v_cvt_pk_bf16_f32 v109, v18, v19
	v_cvt_pk_bf16_f32 v110, v20, v21
	v_cvt_pk_bf16_f32 v111, v22, v23
	global_store_dwordx4 v[14:15], v[108:111], off sc1
	v_lshl_add_u64 v[14:15], s[100:101], 0, v[14:15]
	ds_read_b32 v16, v9 offset:32
	ds_read_b32 v17, v9 offset:164
	ds_read_b32 v18, v9 offset:296
	ds_read_b32 v19, v9 offset:428
	ds_read_b32 v20, v9 offset:560
	ds_read_b32 v21, v9 offset:692
	ds_read_b32 v22, v9 offset:824
	ds_read_b32 v23, v9 offset:956
	s_waitcnt lgkmcnt(0)
	v_cvt_pk_bf16_f32 v112, v16, v17
	v_cvt_pk_bf16_f32 v113, v18, v19
	v_cvt_pk_bf16_f32 v114, v20, v21
	v_cvt_pk_bf16_f32 v115, v22, v23
	global_store_dwordx4 v[14:15], v[112:115], off sc1
	v_lshl_add_u64 v[14:15], s[100:101], 0, v[14:15]
	ds_read_b32 v16, v9 offset:64
	ds_read_b32 v17, v9 offset:196
	ds_read_b32 v18, v9 offset:328
	ds_read_b32 v19, v9 offset:460
	ds_read_b32 v20, v9 offset:592
	ds_read_b32 v21, v9 offset:724
	ds_read_b32 v22, v9 offset:856
	ds_read_b32 v23, v9 offset:988
	s_waitcnt lgkmcnt(0)
	v_cvt_pk_bf16_f32 v116, v16, v17
	v_cvt_pk_bf16_f32 v117, v18, v19
	v_cvt_pk_bf16_f32 v118, v20, v21
	v_cvt_pk_bf16_f32 v119, v22, v23
	global_store_dwordx4 v[14:15], v[116:119], off sc1
	v_lshl_add_u64 v[14:15], s[100:101], 0, v[14:15]
	ds_read_b32 v16, v9 offset:96
	ds_read_b32 v17, v9 offset:228
	ds_read_b32 v18, v9 offset:360
	ds_read_b32 v19, v9 offset:492
	ds_read_b32 v20, v9 offset:624
	ds_read_b32 v21, v9 offset:756
	ds_read_b32 v22, v9 offset:888
	ds_read_b32 v23, v9 offset:1020
	s_waitcnt lgkmcnt(0)
	v_cvt_pk_bf16_f32 v120, v16, v17
	v_cvt_pk_bf16_f32 v121, v18, v19
	v_cvt_pk_bf16_f32 v122, v20, v21
	v_cvt_pk_bf16_f32 v123, v22, v23
	global_store_dwordx4 v[14:15], v[120:123], off sc1
	s_waitcnt vmcnt(4)
	v_mul_f32_e32 v96, v104, v96
	v_mul_f32_e32 v97, v104, v97
	v_mul_f32_e32 v98, v104, v98
	v_mul_f32_e32 v99, v104, v99
	v_mul_f32_e32 v100, v104, v100
	v_mul_f32_e32 v101, v104, v101
	v_mul_f32_e32 v102, v104, v102
	v_mul_f32_e32 v103, v104, v103
	v_mul_f32_e32 v64, v64, v96
	v_mul_f32_e32 v65, v65, v96
	v_mul_f32_e32 v66, v66, v96
	v_mul_f32_e32 v67, v67, v96
	v_mul_f32_e32 v68, v68, v97
	v_mul_f32_e32 v69, v69, v97
	v_mul_f32_e32 v70, v70, v97
	v_mul_f32_e32 v71, v71, v97
	v_mul_f32_e32 v72, v72, v98
	v_mul_f32_e32 v73, v73, v98
	v_mul_f32_e32 v74, v74, v98
	v_mul_f32_e32 v75, v75, v98
	v_mul_f32_e32 v76, v76, v99
	v_mul_f32_e32 v77, v77, v99
	v_mul_f32_e32 v78, v78, v99
	v_mul_f32_e32 v79, v79, v99
	v_mul_f32_e32 v80, v80, v100
	v_mul_f32_e32 v81, v81, v100
	v_mul_f32_e32 v82, v82, v100
	v_mul_f32_e32 v83, v83, v100
	v_mul_f32_e32 v84, v84, v101
	v_mul_f32_e32 v85, v85, v101
	v_mul_f32_e32 v86, v86, v101
	v_mul_f32_e32 v87, v87, v101
	v_mul_f32_e32 v88, v88, v102
	v_mul_f32_e32 v89, v89, v102
	v_mul_f32_e32 v90, v90, v102
	v_mul_f32_e32 v91, v91, v102
	v_mul_f32_e32 v92, v92, v103
	v_mul_f32_e32 v93, v93, v103
	v_mul_f32_e32 v94, v94, v103
	v_mul_f32_e32 v95, v95, v103
	ds_write_b32 v8, v64 offset:0
	ds_write_b32 v8, v65 offset:4
	ds_write_b32 v8, v66 offset:8
	ds_write_b32 v8, v67 offset:12
	ds_write_b32 v8, v68 offset:1056
	ds_write_b32 v8, v69 offset:1060
	ds_write_b32 v8, v70 offset:1064
	ds_write_b32 v8, v71 offset:1068
	ds_write_b32 v8, v72 offset:2112
	ds_write_b32 v8, v73 offset:2116
	ds_write_b32 v8, v74 offset:2120
	ds_write_b32 v8, v75 offset:2124
	ds_write_b32 v8, v76 offset:3168
	ds_write_b32 v8, v77 offset:3172
	ds_write_b32 v8, v78 offset:3176
	ds_write_b32 v8, v79 offset:3180
	ds_write_b32 v8, v80 offset:4224
	ds_write_b32 v8, v81 offset:4228
	ds_write_b32 v8, v82 offset:4232
	ds_write_b32 v8, v83 offset:4236
	ds_write_b32 v8, v84 offset:5280
	ds_write_b32 v8, v85 offset:5284
	ds_write_b32 v8, v86 offset:5288
	ds_write_b32 v8, v87 offset:5292
	ds_write_b32 v8, v88 offset:6336
	ds_write_b32 v8, v89 offset:6340
	ds_write_b32 v8, v90 offset:6344
	ds_write_b32 v8, v91 offset:6348
	ds_write_b32 v8, v92 offset:7392
	ds_write_b32 v8, v93 offset:7396
	ds_write_b32 v8, v94 offset:7400
	ds_write_b32 v8, v95 offset:7404
	s_waitcnt lgkmcnt(0)
	ds_read_b32 v64, v9 offset:0
	ds_read_b32 v65, v9 offset:132
	ds_read_b32 v66, v9 offset:264
	ds_read_b32 v67, v9 offset:396
	ds_read_b32 v68, v9 offset:528
	ds_read_b32 v69, v9 offset:660
	ds_read_b32 v70, v9 offset:792
	ds_read_b32 v71, v9 offset:924
	s_waitcnt lgkmcnt(0)
	v_cvt_pk_bf16_f32 v108, v64, v65
	v_cvt_pk_bf16_f32 v109, v66, v67
	v_cvt_pk_bf16_f32 v110, v68, v69
	v_cvt_pk_bf16_f32 v111, v70, v71
	global_store_dwordx4 v[60:61], v[108:111], off sc1
	v_lshl_add_u64 v[60:61], s[100:101], 0, v[60:61]
	ds_read_b32 v64, v9 offset:32
	ds_read_b32 v65, v9 offset:164
	ds_read_b32 v66, v9 offset:296
	ds_read_b32 v67, v9 offset:428
	ds_read_b32 v68, v9 offset:560
	ds_read_b32 v69, v9 offset:692
	ds_read_b32 v70, v9 offset:824
	ds_read_b32 v71, v9 offset:956
	s_waitcnt lgkmcnt(0)
	v_cvt_pk_bf16_f32 v112, v64, v65
	v_cvt_pk_bf16_f32 v113, v66, v67
	v_cvt_pk_bf16_f32 v114, v68, v69
	v_cvt_pk_bf16_f32 v115, v70, v71
	global_store_dwordx4 v[60:61], v[112:115], off sc1
	v_lshl_add_u64 v[60:61], s[100:101], 0, v[60:61]
	ds_read_b32 v64, v9 offset:64
	ds_read_b32 v65, v9 offset:196
	ds_read_b32 v66, v9 offset:328
	ds_read_b32 v67, v9 offset:460
	ds_read_b32 v68, v9 offset:592
	ds_read_b32 v69, v9 offset:724
	ds_read_b32 v70, v9 offset:856
	ds_read_b32 v71, v9 offset:988
	s_waitcnt lgkmcnt(0)
	v_cvt_pk_bf16_f32 v116, v64, v65
	v_cvt_pk_bf16_f32 v117, v66, v67
	v_cvt_pk_bf16_f32 v118, v68, v69
	v_cvt_pk_bf16_f32 v119, v70, v71
	global_store_dwordx4 v[60:61], v[116:119], off sc1
	v_lshl_add_u64 v[60:61], s[100:101], 0, v[60:61]
	ds_read_b32 v64, v9 offset:96
	ds_read_b32 v65, v9 offset:228
	ds_read_b32 v66, v9 offset:360
	ds_read_b32 v67, v9 offset:492
	ds_read_b32 v68, v9 offset:624
	ds_read_b32 v69, v9 offset:756
	ds_read_b32 v70, v9 offset:888
	ds_read_b32 v71, v9 offset:1020
	s_waitcnt lgkmcnt(0)
	v_cvt_pk_bf16_f32 v120, v64, v65
	v_cvt_pk_bf16_f32 v121, v66, v67
	v_cvt_pk_bf16_f32 v122, v68, v69
	v_cvt_pk_bf16_f32 v123, v70, v71
	global_store_dwordx4 v[60:61], v[120:123], off sc1
	s_add_i32 s35, s38, s39
	s_cmp_lt_i32 s35, s23
	s_cbranch_scc1 .Lcva_loop
	s_branch .LBB0_1426
.Lcva_single:
	s_movk_i32 s100, 0x4000
	s_waitcnt vmcnt(0)
	v_mul_f32_e32 v48, v56, v48
	v_mul_f32_e32 v49, v56, v49
	v_mul_f32_e32 v50, v56, v50
	v_mul_f32_e32 v51, v56, v51
	v_mul_f32_e32 v52, v56, v52
	v_mul_f32_e32 v53, v56, v53
	v_mul_f32_e32 v54, v56, v54
	v_mul_f32_e32 v55, v56, v55
	v_mul_f32_e32 v16, v16, v48
	v_mul_f32_e32 v17, v17, v48
	v_mul_f32_e32 v18, v18, v48
	v_mul_f32_e32 v19, v19, v48
	v_mul_f32_e32 v20, v20, v49
	v_mul_f32_e32 v21, v21, v49
	v_mul_f32_e32 v22, v22, v49
	v_mul_f32_e32 v23, v23, v49
	v_mul_f32_e32 v24, v24, v50
	v_mul_f32_e32 v25, v25, v50
	v_mul_f32_e32 v26, v26, v50
	v_mul_f32_e32 v27, v27, v50
	v_mul_f32_e32 v28, v28, v51
	v_mul_f32_e32 v29, v29, v51
	v_mul_f32_e32 v30, v30, v51
	v_mul_f32_e32 v31, v31, v51
	v_mul_f32_e32 v32, v32, v52
	v_mul_f32_e32 v33, v33, v52
	v_mul_f32_e32 v34, v34, v52
	v_mul_f32_e32 v35, v35, v52
	v_mul_f32_e32 v36, v36, v53
	v_mul_f32_e32 v37, v37, v53
	v_mul_f32_e32 v38, v38, v53
	v_mul_f32_e32 v39, v39, v53
	v_mul_f32_e32 v40, v40, v54
	v_mul_f32_e32 v41, v41, v54
	v_mul_f32_e32 v42, v42, v54
	v_mul_f32_e32 v43, v43, v54
	v_mul_f32_e32 v44, v44, v55
	v_mul_f32_e32 v45, v45, v55
	v_mul_f32_e32 v46, v46, v55
	v_mul_f32_e32 v47, v47, v55
	ds_write_b32 v8, v16 offset:0
	ds_write_b32 v8, v17 offset:4
	ds_write_b32 v8, v18 offset:8
	ds_write_b32 v8, v19 offset:12
	ds_write_b32 v8, v20 offset:1056
	ds_write_b32 v8, v21 offset:1060
	ds_write_b32 v8, v22 offset:1064
	ds_write_b32 v8, v23 offset:1068
	ds_write_b32 v8, v24 offset:2112
	ds_write_b32 v8, v25 offset:2116
	ds_write_b32 v8, v26 offset:2120
	ds_write_b32 v8, v27 offset:2124
	ds_write_b32 v8, v28 offset:3168
	ds_write_b32 v8, v29 offset:3172
	ds_write_b32 v8, v30 offset:3176
	ds_write_b32 v8, v31 offset:3180
	ds_write_b32 v8, v32 offset:4224
	ds_write_b32 v8, v33 offset:4228
	ds_write_b32 v8, v34 offset:4232
	ds_write_b32 v8, v35 offset:4236
	ds_write_b32 v8, v36 offset:5280
	ds_write_b32 v8, v37 offset:5284
	ds_write_b32 v8, v38 offset:5288
	ds_write_b32 v8, v39 offset:5292
	ds_write_b32 v8, v40 offset:6336
	ds_write_b32 v8, v41 offset:6340
	ds_write_b32 v8, v42 offset:6344
	ds_write_b32 v8, v43 offset:6348
	ds_write_b32 v8, v44 offset:7392
	ds_write_b32 v8, v45 offset:7396
	ds_write_b32 v8, v46 offset:7400
	ds_write_b32 v8, v47 offset:7404
	s_waitcnt lgkmcnt(0)
	ds_read_b32 v16, v9 offset:0
	ds_read_b32 v17, v9 offset:132
	ds_read_b32 v18, v9 offset:264
	ds_read_b32 v19, v9 offset:396
	ds_read_b32 v20, v9 offset:528
	ds_read_b32 v21, v9 offset:660
	ds_read_b32 v22, v9 offset:792
	ds_read_b32 v23, v9 offset:924
	s_waitcnt lgkmcnt(0)
	v_cvt_pk_bf16_f32 v108, v16, v17
	v_cvt_pk_bf16_f32 v109, v18, v19
	v_cvt_pk_bf16_f32 v110, v20, v21
	v_cvt_pk_bf16_f32 v111, v22, v23
	global_store_dwordx4 v[14:15], v[108:111], off sc1
	v_lshl_add_u64 v[14:15], s[100:101], 0, v[14:15]
	ds_read_b32 v16, v9 offset:32
	ds_read_b32 v17, v9 offset:164
	ds_read_b32 v18, v9 offset:296
	ds_read_b32 v19, v9 offset:428
	ds_read_b32 v20, v9 offset:560
	ds_read_b32 v21, v9 offset:692
	ds_read_b32 v22, v9 offset:824
	ds_read_b32 v23, v9 offset:956
	s_waitcnt lgkmcnt(0)
	v_cvt_pk_bf16_f32 v112, v16, v17
	v_cvt_pk_bf16_f32 v113, v18, v19
	v_cvt_pk_bf16_f32 v114, v20, v21
	v_cvt_pk_bf16_f32 v115, v22, v23
	global_store_dwordx4 v[14:15], v[112:115], off sc1
	v_lshl_add_u64 v[14:15], s[100:101], 0, v[14:15]
	ds_read_b32 v16, v9 offset:64
	ds_read_b32 v17, v9 offset:196
	ds_read_b32 v18, v9 offset:328
	ds_read_b32 v19, v9 offset:460
	ds_read_b32 v20, v9 offset:592
	ds_read_b32 v21, v9 offset:724
	ds_read_b32 v22, v9 offset:856
	ds_read_b32 v23, v9 offset:988
	s_waitcnt lgkmcnt(0)
	v_cvt_pk_bf16_f32 v116, v16, v17
	v_cvt_pk_bf16_f32 v117, v18, v19
	v_cvt_pk_bf16_f32 v118, v20, v21
	v_cvt_pk_bf16_f32 v119, v22, v23
	global_store_dwordx4 v[14:15], v[116:119], off sc1
	v_lshl_add_u64 v[14:15], s[100:101], 0, v[14:15]
	ds_read_b32 v16, v9 offset:96
	ds_read_b32 v17, v9 offset:228
	ds_read_b32 v18, v9 offset:360
	ds_read_b32 v19, v9 offset:492
	ds_read_b32 v20, v9 offset:624
	ds_read_b32 v21, v9 offset:756
	ds_read_b32 v22, v9 offset:888
	ds_read_b32 v23, v9 offset:1020
	s_waitcnt lgkmcnt(0)
	v_cvt_pk_bf16_f32 v120, v16, v17
	v_cvt_pk_bf16_f32 v121, v18, v19
	v_cvt_pk_bf16_f32 v122, v20, v21
	v_cvt_pk_bf16_f32 v123, v22, v23
	global_store_dwordx4 v[14:15], v[120:123], off sc1
	s_branch .LBB0_1426
